# phase 29 PLE epilogue really skips the unread bf16 copy now (the phase number is read from its spill lane; the earlier test compared a clobbered SGPR)
# speedup vs baseline: 1.0040x; 1.0040x over previous
.LBB0_908:
	s_add_i32 m0, s31, 0x18000
	v_lshl_add_u64 v[12:13], v[12:13], 0, s[16:17]
	s_waitcnt vmcnt(4)
	s_barrier
	global_load_lds_dwordx4 v[12:13], off
	v_lshl_add_u64 v[10:11], v[10:11], 0, s[16:17]
	s_add_i32 m0, s31, 0x1a000
	s_add_i32 s97, s31, 0x8000
	global_load_lds_dwordx4 v[10:11], off
	v_lshl_add_u64 v[8:9], v[8:9], 0, s[16:17]
	s_mov_b32 m0, s97
	s_add_i32 s90, s31, 0xa000
	global_load_lds_dwordx4 v[8:9], off
	v_lshl_add_u64 v[6:7], v[6:7], 0, s[16:17]
	s_mov_b32 m0, s90
	v_lshl_add_u64 v[4:5], v[4:5], 0, s[16:17]
	global_load_lds_dwordx4 v[6:7], off
	s_add_i32 m0, s31, 0x1c000
	v_lshl_add_u64 v[2:3], v[2:3], 0, s[16:17]
	global_load_lds_dwordx4 v[4:5], off
	s_add_i32 m0, s31, 0x1e000
	s_lshr_b32 s91, s94, 6
	global_load_lds_dwordx4 v[2:3], off
	s_and_b32 s4, s4, 3
	s_waitcnt vmcnt(0)
	v_lshl_or_b32 v210, s42, 6, v206
	s_lshl_b32 s42, s42, 13
	v_lshlrev_b32_e32 v2, 2, v206
	s_add_i32 s66, s91, -2
	v_lshl_or_b32 v0, v206, 6, v208
	v_and_b32_e32 v2, 32, v2
	s_cmp_lt_u32 s4, 2
	v_bitop3_b32 v2, v0, s42, v2 bitop3:0xde
	s_cselect_b64 s[42:43], -1, 0
	v_lshl_or_b32 v162, s4, 5, v207
	v_writelane_b32 v253, s42, 57
	s_cmp_eq_u32 s4, 0
	s_waitcnt vmcnt(6)
	v_lshlrev_b32_e32 v0, 2, v162
	v_writelane_b32 v253, s43, 58
	s_cselect_b64 s[42:43], -1, 0
	s_cmp_lg_u64 s[48:49], 0
	v_writelane_b32 v253, s42, 55
	v_lshl_add_u64 v[176:177], s[38:39], 0, v[0:1]
	v_lshlrev_b32_e32 v0, 1, v162
	s_cselect_b64 s[68:69], -1, 0
	v_readlane_b32 s100, v254, 52
	s_cmp_eq_u32 s100, 29
	s_cselect_b64 s[68:69], 0, s[68:69]
	s_cmp_lg_u64 s[56:57], 0
	v_lshl_or_b32 v211, s4, 12, v209
	s_mov_b32 s67, 0
	v_writelane_b32 v253, s43, 56
	v_lshl_add_u64 v[178:179], s[58:59], 0, v[0:1]
	v_lshl_add_u64 v[180:181], s[24:25], 0, v[0:1]
	s_cselect_b64 s[70:71], -1, 0
	v_lshl_add_u64 v[182:183], s[60:61], 0, v[172:173]
	v_lshl_add_u64 v[184:185], s[60:61], 0, v[168:169]
	v_add_u32_e32 v212, 0, v2
	s_barrier
	s_branch .LBB0_910
